# DF attention loop: pipelined K-fragment LDS reads in QK blocks (4 in flight), 3-deep V tr-read rotation in PV blocks
# baseline (speedup 1.0000x reference)
; #define LAS __attribute__((address_space(3)))
; template <int HB> __device__ __forceinline__ void qkt_h(f32x16& p, const LAS unsigned char* Ks, const bf16x8* qr, int r32, int hi) {
;     p = f32x16{};
;     __builtin_amdgcn_s_setprio(1);
; #pragma unroll
;     for (int d0 = 0; d0 < 8; ++d0) { const int cb = (d0 * 16 + hi * 8) * 2;
;         const bf16x8 b0 = *(const LAS bf16x8*)(Ks + KSWZ(32 * HB + r32, cb));
;         p = __builtin_amdgcn_mfma_f32_32x32x16_bf16(b0, qr[d0], p, 0, 0, 0);
;         if (d0 == 3) __builtin_amdgcn_sched_barrier(0); }
;     __builtin_amdgcn_s_setprio(0);
; }
.LBB0_272:
	s_xor_b64 s[34:35], s[34:35], -1
	s_andn2_b64 vcc, exec, s[34:35]
	s_mov_b64 s[34:35], -1
	s_cbranch_vccnz .LBB0_287
	s_add_i32 s37, s37, 1
	s_cmp_gt_i32 s37, s43
	s_mov_b64 s[34:35], 0
	s_cbranch_scc1 .LBB0_287
	v_mov_b32_e32 v0, v179
	s_setprio 1
	v_add_u32_e32 v236, s36, v196
	v_add_u32_e32 v225, v236, v197
	v_add_u32_e32 v226, v236, v198
	v_add_u32_e32 v227, v236, v199
	v_add_u32_e32 v228, v236, v200
	ds_read_b128 v[238:241], v225 offset:8192
	ds_read_b128 v[242:245], v226 offset:8192
	ds_read_b128 v[246:249], v227 offset:8192
	ds_read_b128 v[250:253], v228 offset:8192
	v_add_u32_e32 v229, v236, v201
	v_add_u32_e32 v230, v236, v202
	v_add_u32_e32 v231, v236, v203
	v_add_u32_e32 v232, v236, v204
	s_waitcnt lgkmcnt(3)
	v_mfma_f32_32x32x16_bf16 v[130:145], v[238:241], v[170:173], 0
	ds_read_b128 v[238:241], v229 offset:8192
	s_waitcnt lgkmcnt(3)
	v_mfma_f32_32x32x16_bf16 v[130:145], v[242:245], v[146:149], v[130:145]
	ds_read_b128 v[242:245], v230 offset:8192
	s_waitcnt lgkmcnt(3)
	v_mfma_f32_32x32x16_bf16 v[130:145], v[246:249], v[150:153], v[130:145]
	ds_read_b128 v[246:249], v231 offset:8192
	s_waitcnt lgkmcnt(3)
	v_mfma_f32_32x32x16_bf16 v[130:145], v[250:253], v[154:157], v[130:145]
	ds_read_b128 v[250:253], v232 offset:8192
	s_waitcnt lgkmcnt(3)
	v_mfma_f32_32x32x16_bf16 v[130:145], v[238:241], v[158:161], v[130:145]
	s_waitcnt lgkmcnt(2)
	v_mfma_f32_32x32x16_bf16 v[130:145], v[242:245], v[162:165], v[130:145]
	s_waitcnt lgkmcnt(1)
	v_mfma_f32_32x32x16_bf16 v[130:145], v[246:249], v[166:169], v[130:145]
	s_waitcnt lgkmcnt(0)
	v_mfma_f32_32x32x16_bf16 v[130:145], v[250:253], v[174:177], v[130:145]
	s_setprio 0
	v_cvt_f32_i32_e32 v233, v222
	v_sub_f32_e32 v234, v233, v206
	v_sub_f32_e32 v236, v233, v207
	v_mul_f32_e64 v235, |v234|, -v194
	v_mul_f32_e64 v234, |v236|, -v194
	s_nop 5
	v_fmac_f32_e32 v234, 0x3e0293ee, v131
	v_sub_f32_e32 v131, v233, v208
	v_mul_f32_e64 v236, |v131|, -v194
	v_sub_f32_e32 v131, v233, v209
	v_mul_f32_e64 v238, |v131|, -v194
	v_sub_f32_e32 v131, v233, v210
	v_mul_f32_e64 v237, |v131|, -v194
	v_sub_f32_e32 v131, v233, v211
	v_mul_f32_e64 v239, |v131|, -v194
	v_sub_f32_e32 v131, v233, v212
	v_mul_f32_e64 v240, |v131|, -v194
	v_sub_f32_e32 v131, v233, v213
	v_mul_f32_e64 v242, |v131|, -v194
	v_sub_f32_e32 v131, v233, v214
	v_mul_f32_e64 v241, |v131|, -v194
	v_sub_f32_e32 v131, v233, v215
	v_fmac_f32_e32 v235, 0x3e0293ee, v130
	v_mul_f32_e64 v243, |v131|, -v194
	v_sub_f32_e32 v131, v233, v216
	v_max3_f32 v130, v235, s86, v234
	v_fmac_f32_e32 v236, 0x3e0293ee, v132
	v_fmac_f32_e32 v238, 0x3e0293ee, v133
	v_mul_f32_e64 v244, |v131|, -v194
	v_sub_f32_e32 v131, v233, v217
	v_max3_f32 v130, v130, v236, v238
	v_fmac_f32_e32 v237, 0x3e0293ee, v134
	v_fmac_f32_e32 v239, 0x3e0293ee, v135
	v_mul_f32_e64 v246, |v131|, -v194
	v_sub_f32_e32 v131, v233, v218
	v_max3_f32 v130, v130, v237, v239
	v_fmac_f32_e32 v240, 0x3e0293ee, v136
	v_fmac_f32_e32 v242, 0x3e0293ee, v137
	v_mul_f32_e64 v245, |v131|, -v194
	v_sub_f32_e32 v131, v233, v219
	v_max3_f32 v130, v130, v240, v242
	v_fmac_f32_e32 v241, 0x3e0293ee, v138
	v_fmac_f32_e32 v243, 0x3e0293ee, v139
	v_mul_f32_e64 v247, |v131|, -v194
	v_sub_f32_e32 v131, v233, v220
	v_max3_f32 v130, v130, v241, v243
	v_fmac_f32_e32 v244, 0x3e0293ee, v140
	v_fmac_f32_e32 v246, 0x3e0293ee, v141
	v_mul_f32_e64 v248, |v131|, -v194
	v_sub_f32_e32 v131, v233, v221
	v_max3_f32 v130, v130, v244, v246
	v_fmac_f32_e32 v245, 0x3e0293ee, v142
	v_fmac_f32_e32 v247, 0x3e0293ee, v143
	v_mul_f32_e64 v249, |v131|, -v194
	v_max3_f32 v130, v130, v245, v247
	v_fmac_f32_e32 v248, 0x3e0293ee, v144
	v_fmac_f32_e32 v249, 0x3e0293ee, v145
	v_max3_f32 v130, v130, v248, v249
	v_mov_b32_e32 v131, v130
	s_nop 1
	v_permlane32_swap_b32_e32 v130, v131
	v_max_f32_e32 v131, v131, v131
	v_max_f32_e32 v130, v130, v130
	v_max_f32_e32 v130, v130, v131
	v_cmp_gt_f32_e32 vcc, v130, v224
	s_cbranch_vccz .LBB0_278
	v_max_f32_e32 v130, v130, v130
	v_max_f32_e32 v131, v224, v224
	v_max_f32_e32 v233, v131, v130
	v_sub_f32_e32 v130, v224, v233
	v_exp_f32_e32 v130, v130
	s_and_saveexec_b64 s[34:35], s[0:1]
	ds_write_b32 v205, v130
	s_or_b64 exec, exec, s[34:35]
	s_waitcnt lgkmcnt(0)
	v_add_u32_e32 v142, s48, v195
	v_mul_f32_e32 v223, v223, v130
	ds_read_b128 v[130:133], v142
	ds_read_b128 v[134:137], v142 offset:32
	ds_read_b128 v[138:141], v142 offset:64
	ds_read_b128 v[142:145], v142 offset:96
	s_waitcnt lgkmcnt(0)
	v_pk_mul_f32 v[4:5], v[4:5], v[132:133]
	v_pk_mul_f32 v[6:7], v[6:7], v[134:135]
	v_pk_mul_f32 v[10:11], v[10:11], v[138:139]
	v_pk_mul_f32 v[14:15], v[14:15], v[142:143]
	v_pk_mul_f32 v[16:17], v[16:17], v[144:145]
	v_pk_mul_f32 v[12:13], v[12:13], v[140:141]
	v_pk_mul_f32 v[8:9], v[8:9], v[136:137]
	v_pk_mul_f32 v[2:3], v[2:3], v[130:131]
	v_pk_mul_f32 v[30:31], v[30:31], v[142:143]
	v_pk_mul_f32 v[26:27], v[26:27], v[138:139]
	v_pk_mul_f32 v[22:23], v[22:23], v[134:135]
	v_pk_mul_f32 v[32:33], v[32:33], v[144:145]
	v_pk_mul_f32 v[28:29], v[28:29], v[140:141]
	v_pk_mul_f32 v[24:25], v[24:25], v[136:137]
	v_pk_mul_f32 v[20:21], v[20:21], v[132:133]
	v_pk_mul_f32 v[18:19], v[18:19], v[130:131]
	v_pk_mul_f32 v[46:47], v[46:47], v[142:143]
	v_pk_mul_f32 v[42:43], v[42:43], v[138:139]
	v_pk_mul_f32 v[38:39], v[38:39], v[134:135]
	v_pk_mul_f32 v[48:49], v[48:49], v[144:145]
	v_pk_mul_f32 v[44:45], v[44:45], v[140:141]
	v_pk_mul_f32 v[40:41], v[40:41], v[136:137]
	v_pk_mul_f32 v[36:37], v[36:37], v[132:133]
	v_pk_mul_f32 v[34:35], v[34:35], v[130:131]
	v_pk_mul_f32 v[62:63], v[62:63], v[142:143]
	v_pk_mul_f32 v[58:59], v[58:59], v[138:139]
	v_pk_mul_f32 v[54:55], v[54:55], v[134:135]
	v_pk_mul_f32 v[64:65], v[64:65], v[144:145]
	v_pk_mul_f32 v[60:61], v[60:61], v[140:141]
	v_pk_mul_f32 v[56:57], v[56:57], v[136:137]
	v_pk_mul_f32 v[52:53], v[52:53], v[132:133]
	v_pk_mul_f32 v[50:51], v[50:51], v[130:131]
	v_pk_mul_f32 v[78:79], v[78:79], v[142:143]
	v_pk_mul_f32 v[74:75], v[74:75], v[138:139]
	v_pk_mul_f32 v[70:71], v[70:71], v[134:135]
	v_pk_mul_f32 v[80:81], v[80:81], v[144:145]
	v_pk_mul_f32 v[76:77], v[76:77], v[140:141]
	v_pk_mul_f32 v[72:73], v[72:73], v[136:137]
	v_pk_mul_f32 v[68:69], v[68:69], v[132:133]
	v_pk_mul_f32 v[66:67], v[66:67], v[130:131]
	v_pk_mul_f32 v[94:95], v[94:95], v[142:143]
	v_pk_mul_f32 v[90:91], v[90:91], v[138:139]
	v_pk_mul_f32 v[86:87], v[86:87], v[134:135]
	v_pk_mul_f32 v[96:97], v[96:97], v[144:145]
	v_pk_mul_f32 v[92:93], v[92:93], v[140:141]
	v_pk_mul_f32 v[88:89], v[88:89], v[136:137]
	v_pk_mul_f32 v[84:85], v[84:85], v[132:133]
	v_pk_mul_f32 v[82:83], v[82:83], v[130:131]
	v_pk_mul_f32 v[110:111], v[110:111], v[142:143]
	v_pk_mul_f32 v[106:107], v[106:107], v[138:139]
	v_pk_mul_f32 v[102:103], v[102:103], v[134:135]
	v_pk_mul_f32 v[112:113], v[112:113], v[144:145]
	v_pk_mul_f32 v[108:109], v[108:109], v[140:141]
	v_pk_mul_f32 v[104:105], v[104:105], v[136:137]
	v_pk_mul_f32 v[100:101], v[100:101], v[132:133]
	v_pk_mul_f32 v[98:99], v[98:99], v[130:131]
	v_pk_mul_f32 v[126:127], v[126:127], v[142:143]
	v_pk_mul_f32 v[122:123], v[122:123], v[138:139]
	v_pk_mul_f32 v[118:119], v[118:119], v[134:135]
	v_pk_mul_f32 v[128:129], v[128:129], v[144:145]
	v_pk_mul_f32 v[124:125], v[124:125], v[140:141]
	v_pk_mul_f32 v[120:121], v[120:121], v[136:137]
	v_pk_mul_f32 v[116:117], v[116:117], v[132:133]
	v_pk_mul_f32 v[114:115], v[114:115], v[130:131]
	s_branch .LBB0_279

; #define TR4(g, D0, X) const s16x4 l0_##g = tr_read<v_rd_off(D0, KS0, 0) + X>(vb), h0_##g = tr_read<v_rd_off(D0, KS0, 1) + X>(vb), l1_##g = tr_read<v_rd_off(D0, KS0 + 1, 0) + X>(vb), h1_##g = tr_read<v_rd_off(D0, KS0 + 1, 1) + X>(vb)
; #define MM2(g, od) do { __builtin_amdgcn_s_setprio(1); od = __builtin_amdgcn_mfma_f32_32x32x16_bf16(paA, PKV(l0_##g, h0_##g), od, 0, 0, 0); od = __builtin_amdgcn_mfma_f32_32x32x16_bf16(paB, PKV(l1_##g, h1_##g), od, 0, 0, 0); __builtin_amdgcn_s_setprio(0); } while (0)
; #define WAITL(n) do { asm volatile("s_waitcnt lgkmcnt(" #n ")" ::: "memory"); __builtin_amdgcn_sched_barrier(0); } while (0)
; template <int HB, bool WIDE> __device__ __forceinline__ void pv_pipe(f32x16* o, int vb, bf16x8 paA, bf16x8 paB) {
;     constexpr int KS0 = 2 * HB;
;     ...
;     TR4(0, 0, 0); TR4(1, 1, 0);
;     WAITL(4); MM2(0, o[0]); TR4(2, 2, 0);
;     WAITL(4); MM2(1, o[1]); TR4(3, 3, 0);
;     if constexpr (WIDE) {
;         WAITL(4); MM2(2, o[2]); TR4(4, 0, 16384);
;         WAITL(4); MM2(3, o[3]); TR4(5, 1, 16384);
;         WAITL(4); MM2(4, o[4]); TR4(6, 2, 16384);
;         WAITL(4); MM2(5, o[5]); TR4(7, 3, 16384);
;         WAITL(4); MM2(6, o[6]);
;         WAITL(0); MM2(7, o[7]);
;     } else {
;         WAITL(4); MM2(2, o[2]);
;         WAITL(0); MM2(3, o[3]);
;     }
.LBB0_279:
	v_lshlrev_b32_e32 v131, 4, v0
	v_lshlrev_b32_e32 v130, 3, v0
	v_and_b32_e32 v131, 0xc0, v131
	v_lshlrev_b32_e32 v0, 1, v0
	v_and_or_b32 v131, v130, 24, v131
	v_and_b32_e32 v0, 32, v0
	v_and_b32_e32 v130, 0x100, v130
	v_or3_b32 v0, v131, v0, v130
	v_sub_f32_e32 v130, v235, v233
	v_exp_f32_e32 v130, v130
	v_sub_f32_e32 v131, v234, v233
	v_exp_f32_e32 v131, v131
	v_sub_f32_e32 v132, v236, v233
	v_exp_f32_e32 v132, v132
	v_sub_f32_e32 v133, v238, v233
	v_exp_f32_e32 v133, v133
	v_sub_f32_e32 v135, v237, v233
	v_add_f32_e32 v134, 0, v130
	v_exp_f32_e32 v135, v135
	v_sub_f32_e32 v136, v239, v233
	v_add_f32_e32 v134, v131, v134
	v_exp_f32_e32 v136, v136
	v_sub_f32_e32 v137, v240, v233
	v_add_f32_e32 v134, v132, v134
	v_exp_f32_e32 v137, v137
	v_sub_f32_e32 v138, v242, v233
	v_add_f32_e32 v134, v133, v134
	v_exp_f32_e32 v138, v138
	v_sub_f32_e32 v139, v241, v233
	v_add_f32_e32 v134, v135, v134
	v_exp_f32_e32 v139, v139
	v_sub_f32_e32 v140, v243, v233
	v_add_f32_e32 v134, v136, v134
	v_exp_f32_e32 v140, v140
	v_sub_f32_e32 v141, v244, v233
	v_add_f32_e32 v134, v137, v134
	v_exp_f32_e32 v141, v141
	v_sub_f32_e32 v142, v246, v233
	v_add_f32_e32 v134, v138, v134
	v_exp_f32_e32 v142, v142
	v_sub_f32_e32 v143, v245, v233
	v_add_f32_e32 v134, v139, v134
	v_exp_f32_e32 v143, v143
	v_sub_f32_e32 v144, v247, v233
	v_add_f32_e32 v134, v140, v134
	v_exp_f32_e32 v144, v144
	v_sub_f32_e32 v145, v248, v233
	v_add_f32_e32 v134, v141, v134
	v_exp_f32_e32 v145, v145
	v_sub_f32_e32 v224, v249, v233
	v_add_f32_e32 v134, v142, v134
	v_exp_f32_e32 v224, v224
	v_add_f32_e32 v134, v143, v134
	v_add_f32_e32 v134, v144, v134
	v_add_f32_e32 v134, v145, v134
	v_add_f32_e32 v134, v224, v134
	s_add_i32 s34, s36, 0
	v_mov_b32_e32 v234, v134
	s_add_i32 s34, s34, 0x8000
	s_nop 0
	v_permlane32_swap_b32_e32 v134, v234
	v_add_u32_e32 v0, s34, v0
	v_add_f32_e32 v242, v134, v234
	v_cvt_pk_bf16_f32 v130, v130, v131
	v_cvt_pk_bf16_f32 v131, v132, v133
	v_cvt_pk_bf16_f32 v133, v137, v138
	v_cvt_pk_bf16_f32 v134, v139, v140
	ds_read_b64_tr_b16 v[138:139], v0 offset:0x2000
	v_cvt_pk_bf16_f32 v132, v135, v136
	v_cvt_pk_bf16_f32 v135, v141, v142
	ds_read_b64_tr_b16 v[140:141], v0 offset:0x2800
	v_cvt_pk_bf16_f32 v136, v143, v144
	ds_read_b64_tr_b16 v[142:143], v0 offset:0x3000
	v_cvt_pk_bf16_f32 v137, v145, v224
	ds_read_b64_tr_b16 v[144:145], v0 offset:0x3800
	ds_read_b64_tr_b16 v[234:235], v0 offset:0x2200
	ds_read_b64_tr_b16 v[236:237], v0 offset:0x2a00
	ds_read_b64_tr_b16 v[238:239], v0 offset:0x3200
	ds_read_b64_tr_b16 v[240:241], v0 offset:0x3a00
	ds_read_b64_tr_b16 v[244:245], v0 offset:0x2400
	ds_read_b64_tr_b16 v[246:247], v0 offset:0x2c00
	ds_read_b64_tr_b16 v[248:249], v0 offset:0x3400
	ds_read_b64_tr_b16 v[250:251], v0 offset:0x3c00
	s_waitcnt lgkmcnt(8)
	v_permlane32_swap_b32_e32 v130, v132
	v_permlane32_swap_b32_e32 v131, v133
	v_permlane32_swap_b32_e32 v134, v136
	v_permlane32_swap_b32_e32 v135, v137
	s_setprio 1
	v_mfma_f32_32x32x16_bf16 v[2:17], v[130:133], v[138:141], v[2:17]
	v_mfma_f32_32x32x16_bf16 v[2:17], v[134:137], v[142:145], v[2:17]
	s_setprio 0
	ds_read_b64_tr_b16 v[138:139], v0 offset:0x2600
	ds_read_b64_tr_b16 v[140:141], v0 offset:0x2e00
	ds_read_b64_tr_b16 v[142:143], v0 offset:0x3600
	ds_read_b64_tr_b16 v[144:145], v0 offset:0x3e00
	s_waitcnt lgkmcnt(8)
	s_setprio 1
	v_mfma_f32_32x32x16_bf16 v[18:33], v[130:133], v[234:237], v[18:33]
	v_mfma_f32_32x32x16_bf16 v[18:33], v[134:137], v[238:241], v[18:33]
	s_setprio 0
	ds_read_b64_tr_b16 v[234:235], v0 offset:0x6000
	ds_read_b64_tr_b16 v[236:237], v0 offset:0x6800
	ds_read_b64_tr_b16 v[238:239], v0 offset:0x7000
	ds_read_b64_tr_b16 v[240:241], v0 offset:0x7800
	s_waitcnt lgkmcnt(8)
	s_setprio 1
	v_mfma_f32_32x32x16_bf16 v[34:49], v[130:133], v[244:247], v[34:49]
	v_mfma_f32_32x32x16_bf16 v[34:49], v[134:137], v[248:251], v[34:49]
	s_setprio 0
	ds_read_b64_tr_b16 v[244:245], v0 offset:0x6200
	ds_read_b64_tr_b16 v[246:247], v0 offset:0x6a00
	ds_read_b64_tr_b16 v[248:249], v0 offset:0x7200
	ds_read_b64_tr_b16 v[250:251], v0 offset:0x7a00
	s_waitcnt lgkmcnt(8)
	s_setprio 1
	v_mfma_f32_32x32x16_bf16 v[50:65], v[130:133], v[138:141], v[50:65]
	v_mfma_f32_32x32x16_bf16 v[50:65], v[134:137], v[142:145], v[50:65]
	s_setprio 0
	ds_read_b64_tr_b16 v[138:139], v0 offset:0x6400
	ds_read_b64_tr_b16 v[140:141], v0 offset:0x6c00
	ds_read_b64_tr_b16 v[142:143], v0 offset:0x7400
	ds_read_b64_tr_b16 v[144:145], v0 offset:0x7c00
	s_waitcnt lgkmcnt(8)
	s_setprio 1
	v_mfma_f32_32x32x16_bf16 v[66:81], v[130:133], v[234:237], v[66:81]
	v_mfma_f32_32x32x16_bf16 v[66:81], v[134:137], v[238:241], v[66:81]
	s_setprio 0
	ds_read_b64_tr_b16 v[234:235], v0 offset:0x6600
	ds_read_b64_tr_b16 v[236:237], v0 offset:0x6e00
	ds_read_b64_tr_b16 v[238:239], v0 offset:0x7600
	ds_read_b64_tr_b16 v[240:241], v0 offset:0x7e00
	s_waitcnt lgkmcnt(8)
	s_setprio 1
	v_mfma_f32_32x32x16_bf16 v[82:97], v[130:133], v[244:247], v[82:97]
	v_mfma_f32_32x32x16_bf16 v[82:97], v[134:137], v[248:251], v[82:97]
	s_setprio 0
	s_waitcnt lgkmcnt(4)
	s_setprio 1
	v_mfma_f32_32x32x16_bf16 v[98:113], v[130:133], v[138:141], v[98:113]
	v_mfma_f32_32x32x16_bf16 v[98:113], v[134:137], v[142:145], v[98:113]
	s_setprio 0
	s_waitcnt lgkmcnt(0)
	s_setprio 1
	v_mfma_f32_32x32x16_bf16 v[114:129], v[130:133], v[234:237], v[114:129]
	v_mfma_f32_32x32x16_bf16 v[114:129], v[134:137], v[238:241], v[114:129]
	s_setprio 0
	s_setprio 1
	ds_read_b128 v[130:133], v225
	ds_read_b128 v[234:237], v226
	ds_read_b128 v[238:241], v227
	ds_read_b128 v[244:247], v228
	s_waitcnt lgkmcnt(3)
	v_mfma_f32_32x32x16_bf16 v[130:145], v[130:133], v[170:173], 0
	ds_read_b128 v[224:227], v229
	s_waitcnt lgkmcnt(3)
; #define LAS __attribute__((address_space(3)))
; template <int HB> __device__ __forceinline__ void qkt_h(f32x16& p, const LAS unsigned char* Ks, const bf16x8* qr, int r32, int hi) {
;     p = f32x16{};
;     __builtin_amdgcn_s_setprio(1);
; #pragma unroll
;     for (int d0 = 0; d0 < 8; ++d0) { const int cb = (d0 * 16 + hi * 8) * 2;
;         const bf16x8 b0 = *(const LAS bf16x8*)(Ks + KSWZ(32 * HB + r32, cb));
;         p = __builtin_amdgcn_mfma_f32_32x32x16_bf16(b0, qr[d0], p, 0, 0, 0);
;         if (d0 == 3) __builtin_amdgcn_sched_barrier(0); }
;     __builtin_amdgcn_s_setprio(0);
; }
	v_mfma_f32_32x32x16_bf16 v[130:145], v[234:237], v[146:149], v[130:145]
	ds_read_b128 v[234:237], v230
	s_waitcnt lgkmcnt(3)
	v_mfma_f32_32x32x16_bf16 v[130:145], v[238:241], v[150:153], v[130:145]
	ds_read_b128 v[238:241], v231
	s_waitcnt lgkmcnt(3)
	v_mfma_f32_32x32x16_bf16 v[130:145], v[244:247], v[154:157], v[130:145]
	ds_read_b128 v[244:247], v232
	s_waitcnt lgkmcnt(3)
	v_mfma_f32_32x32x16_bf16 v[130:145], v[224:227], v[158:161], v[130:145]
	s_waitcnt lgkmcnt(2)
	v_mfma_f32_32x32x16_bf16 v[130:145], v[234:237], v[162:165], v[130:145]
	s_waitcnt lgkmcnt(1)
	v_mfma_f32_32x32x16_bf16 v[130:145], v[238:241], v[166:169], v[130:145]
	s_waitcnt lgkmcnt(0)
	v_mfma_f32_32x32x16_bf16 v[130:145], v[244:247], v[174:177], v[130:145]
	s_setprio 0
	v_add_u32_e32 v250, 32, v222
	v_cvt_f32_i32_e32 v224, v250
	v_add_f32_e32 v223, v223, v242
	v_sub_f32_e32 v225, v224, v206
	v_sub_f32_e32 v227, v224, v207
	v_mul_f32_e64 v226, |v225|, -v194
	v_mul_f32_e64 v225, |v227|, -v194
	s_nop 4
	v_fmac_f32_e32 v225, 0x3e0293ee, v131
	v_sub_f32_e32 v131, v224, v208
	v_mul_f32_e64 v227, |v131|, -v194
	v_sub_f32_e32 v131, v224, v209
	v_mul_f32_e64 v229, |v131|, -v194
	v_sub_f32_e32 v131, v224, v210
	v_mul_f32_e64 v228, |v131|, -v194
	v_sub_f32_e32 v131, v224, v211
	v_mul_f32_e64 v230, |v131|, -v194
	v_sub_f32_e32 v131, v224, v212
	v_mul_f32_e64 v231, |v131|, -v194
	v_sub_f32_e32 v131, v224, v213
	v_mul_f32_e64 v234, |v131|, -v194
	v_sub_f32_e32 v131, v224, v214
	v_mul_f32_e64 v232, |v131|, -v194
	v_sub_f32_e32 v131, v224, v215
	v_fmac_f32_e32 v226, 0x3e0293ee, v130
	v_mul_f32_e64 v235, |v131|, -v194
	v_sub_f32_e32 v131, v224, v216
	v_max3_f32 v130, v226, s86, v225
	v_fmac_f32_e32 v227, 0x3e0293ee, v132
	v_fmac_f32_e32 v229, 0x3e0293ee, v133
	v_mul_f32_e64 v236, |v131|, -v194
	v_sub_f32_e32 v131, v224, v217
	v_max3_f32 v130, v130, v227, v229
	v_fmac_f32_e32 v228, 0x3e0293ee, v134
	v_fmac_f32_e32 v230, 0x3e0293ee, v135
	v_mul_f32_e64 v238, |v131|, -v194
	v_sub_f32_e32 v131, v224, v218
	v_max3_f32 v130, v130, v228, v230
	v_fmac_f32_e32 v231, 0x3e0293ee, v136
	v_fmac_f32_e32 v234, 0x3e0293ee, v137
	v_mul_f32_e64 v237, |v131|, -v194
	v_sub_f32_e32 v131, v224, v219
	v_max3_f32 v130, v130, v231, v234
	v_fmac_f32_e32 v232, 0x3e0293ee, v138
	v_fmac_f32_e32 v235, 0x3e0293ee, v139
	v_mul_f32_e64 v239, |v131|, -v194
	v_sub_f32_e32 v131, v224, v220
	v_max3_f32 v130, v130, v232, v235
	v_fmac_f32_e32 v236, 0x3e0293ee, v140
	v_fmac_f32_e32 v238, 0x3e0293ee, v141
	v_mul_f32_e64 v240, |v131|, -v194
	v_sub_f32_e32 v131, v224, v221
	v_max3_f32 v130, v130, v236, v238
	v_fmac_f32_e32 v237, 0x3e0293ee, v142
	v_fmac_f32_e32 v239, 0x3e0293ee, v143
	v_mul_f32_e64 v241, |v131|, -v194
	v_max3_f32 v130, v130, v237, v239
	v_fmac_f32_e32 v240, 0x3e0293ee, v144
	v_fmac_f32_e32 v241, 0x3e0293ee, v145
	v_max3_f32 v130, v130, v240, v241
	v_mov_b32_e32 v131, v130
	s_nop 1
	v_permlane32_swap_b32_e32 v130, v131
	v_max_f32_e32 v131, v131, v131
	v_max_f32_e32 v130, v130, v130
	v_max_f32_e32 v130, v130, v131
	v_cmp_gt_f32_e32 vcc, v130, v233
	s_cbranch_vccz .LBB0_283
	v_max_f32_e32 v130, v130, v130
	v_max_f32_e32 v131, v233, v233
	v_max_f32_e32 v224, v131, v130
	v_sub_f32_e32 v130, v233, v224
	v_exp_f32_e32 v233, v130
	s_and_saveexec_b64 s[34:35], s[0:1]
	ds_write_b32 v205, v233
	s_or_b64 exec, exec, s[34:35]
	s_waitcnt lgkmcnt(0)
	v_add_u32_e32 v130, s48, v195
	ds_read_b128 v[142:145], v130 offset:96
	ds_read_b128 v[138:141], v130 offset:64
	ds_read_b128 v[134:137], v130 offset:32
	ds_read_b128 v[130:133], v130
	v_mul_f32_e32 v223, v223, v233
	s_waitcnt lgkmcnt(0)
	v_pk_mul_f32 v[14:15], v[14:15], v[142:143]
	v_pk_mul_f32 v[10:11], v[10:11], v[138:139]
	v_pk_mul_f32 v[6:7], v[6:7], v[134:135]
	v_pk_mul_f32 v[16:17], v[16:17], v[144:145]
	v_pk_mul_f32 v[12:13], v[12:13], v[140:141]
	v_pk_mul_f32 v[8:9], v[8:9], v[136:137]
	v_pk_mul_f32 v[4:5], v[4:5], v[132:133]
	v_pk_mul_f32 v[2:3], v[2:3], v[130:131]
	v_pk_mul_f32 v[30:31], v[30:31], v[142:143]
	v_pk_mul_f32 v[26:27], v[26:27], v[138:139]
	v_pk_mul_f32 v[22:23], v[22:23], v[134:135]
	v_pk_mul_f32 v[32:33], v[32:33], v[144:145]
	v_pk_mul_f32 v[28:29], v[28:29], v[140:141]
	v_pk_mul_f32 v[24:25], v[24:25], v[136:137]
	v_pk_mul_f32 v[20:21], v[20:21], v[132:133]
	v_pk_mul_f32 v[18:19], v[18:19], v[130:131]
	v_pk_mul_f32 v[46:47], v[46:47], v[142:143]
	v_pk_mul_f32 v[42:43], v[42:43], v[138:139]
	v_pk_mul_f32 v[38:39], v[38:39], v[134:135]
	v_pk_mul_f32 v[48:49], v[48:49], v[144:145]
	v_pk_mul_f32 v[44:45], v[44:45], v[140:141]
	v_pk_mul_f32 v[40:41], v[40:41], v[136:137]
	v_pk_mul_f32 v[36:37], v[36:37], v[132:133]
	v_pk_mul_f32 v[34:35], v[34:35], v[130:131]
	v_pk_mul_f32 v[62:63], v[62:63], v[142:143]
	v_pk_mul_f32 v[58:59], v[58:59], v[138:139]
	v_pk_mul_f32 v[54:55], v[54:55], v[134:135]
	v_pk_mul_f32 v[64:65], v[64:65], v[144:145]
	v_pk_mul_f32 v[60:61], v[60:61], v[140:141]
	v_pk_mul_f32 v[56:57], v[56:57], v[136:137]
	v_pk_mul_f32 v[52:53], v[52:53], v[132:133]
	v_pk_mul_f32 v[50:51], v[50:51], v[130:131]
	v_pk_mul_f32 v[78:79], v[78:79], v[142:143]
	v_pk_mul_f32 v[74:75], v[74:75], v[138:139]
	v_pk_mul_f32 v[70:71], v[70:71], v[134:135]
	v_pk_mul_f32 v[80:81], v[80:81], v[144:145]
	v_pk_mul_f32 v[76:77], v[76:77], v[140:141]
	v_pk_mul_f32 v[72:73], v[72:73], v[136:137]
	v_pk_mul_f32 v[68:69], v[68:69], v[132:133]
	v_pk_mul_f32 v[66:67], v[66:67], v[130:131]
	v_pk_mul_f32 v[94:95], v[94:95], v[142:143]
	v_pk_mul_f32 v[90:91], v[90:91], v[138:139]
	v_pk_mul_f32 v[86:87], v[86:87], v[134:135]
	v_pk_mul_f32 v[96:97], v[96:97], v[144:145]
	v_pk_mul_f32 v[92:93], v[92:93], v[140:141]
	v_pk_mul_f32 v[88:89], v[88:89], v[136:137]
	v_pk_mul_f32 v[84:85], v[84:85], v[132:133]
	v_pk_mul_f32 v[82:83], v[82:83], v[130:131]
	v_pk_mul_f32 v[110:111], v[110:111], v[142:143]
	v_pk_mul_f32 v[106:107], v[106:107], v[138:139]
	v_pk_mul_f32 v[102:103], v[102:103], v[134:135]
	v_pk_mul_f32 v[112:113], v[112:113], v[144:145]
	v_pk_mul_f32 v[108:109], v[108:109], v[140:141]
	v_pk_mul_f32 v[104:105], v[104:105], v[136:137]
	v_pk_mul_f32 v[100:101], v[100:101], v[132:133]
	v_pk_mul_f32 v[98:99], v[98:99], v[130:131]
	v_pk_mul_f32 v[126:127], v[126:127], v[142:143]
	v_pk_mul_f32 v[122:123], v[122:123], v[138:139]
	v_pk_mul_f32 v[118:119], v[118:119], v[134:135]
	v_pk_mul_f32 v[128:129], v[128:129], v[144:145]
	v_pk_mul_f32 v[124:125], v[124:125], v[140:141]
	v_pk_mul_f32 v[120:121], v[120:121], v[136:137]
	v_pk_mul_f32 v[116:117], v[116:117], v[132:133]
	v_pk_mul_f32 v[114:115], v[114:115], v[130:131]
	s_branch .LBB0_284

; #define TR4(g, D0, X) const s16x4 l0_##g = tr_read<v_rd_off(D0, KS0, 0) + X>(vb), h0_##g = tr_read<v_rd_off(D0, KS0, 1) + X>(vb), l1_##g = tr_read<v_rd_off(D0, KS0 + 1, 0) + X>(vb), h1_##g = tr_read<v_rd_off(D0, KS0 + 1, 1) + X>(vb)
; #define MM2(g, od) do { __builtin_amdgcn_s_setprio(1); od = __builtin_amdgcn_mfma_f32_32x32x16_bf16(paA, PKV(l0_##g, h0_##g), od, 0, 0, 0); od = __builtin_amdgcn_mfma_f32_32x32x16_bf16(paB, PKV(l1_##g, h1_##g), od, 0, 0, 0); __builtin_amdgcn_s_setprio(0); } while (0)
; #define WAITL(n) do { asm volatile("s_waitcnt lgkmcnt(" #n ")" ::: "memory"); __builtin_amdgcn_sched_barrier(0); } while (0)
; template <int HB, bool WIDE> __device__ __forceinline__ void pv_pipe(f32x16* o, int vb, bf16x8 paA, bf16x8 paB) {
;     constexpr int KS0 = 2 * HB;
;     ...
;     TR4(0, 0, 0); TR4(1, 1, 0);
;     WAITL(4); MM2(0, o[0]); TR4(2, 2, 0);
;     WAITL(4); MM2(1, o[1]); TR4(3, 3, 0);
;     if constexpr (WIDE) {
;         WAITL(4); MM2(2, o[2]); TR4(4, 0, 16384);
;         WAITL(4); MM2(3, o[3]); TR4(5, 1, 16384);
;         WAITL(4); MM2(4, o[4]); TR4(6, 2, 16384);
;         WAITL(4); MM2(5, o[5]); TR4(7, 3, 16384);
;         WAITL(4); MM2(6, o[6]);
;         WAITL(0); MM2(7, o[7]);
;     } else {
;         WAITL(4); MM2(2, o[2]);
;         WAITL(0); MM2(3, o[3]);
;     }
; __device__ __forceinline__ void df_unit(LAS unsigned char* lds, const bf16_t* qkv, bf16_t* attout, const float* subg, int b_, int h_, int qb_, int wid, int) {
;     ...
;             DF_HALF(1); DF_HALF(0);
;     ...
;             if (can_exit) done = __all(li_l[r32] - slope2 * (float)(q0 + r32 - j * 64 + 1) - m < -150.0f);
.LBB0_284:
	v_sub_f32_e32 v130, v226, v224
	v_exp_f32_e32 v132, v130
	v_sub_f32_e32 v130, v225, v224
	v_exp_f32_e32 v133, v130
	v_sub_f32_e32 v130, v227, v224
	v_exp_f32_e32 v134, v130
	v_sub_f32_e32 v130, v229, v224
	v_exp_f32_e32 v135, v130
	v_sub_f32_e32 v131, v228, v224
	v_add_f32_e32 v130, 0, v132
	v_exp_f32_e32 v136, v131
	v_sub_f32_e32 v131, v230, v224
	v_add_f32_e32 v130, v133, v130
	v_exp_f32_e32 v137, v131
	v_sub_f32_e32 v131, v231, v224
	v_add_f32_e32 v130, v134, v130
	v_exp_f32_e32 v138, v131
	v_sub_f32_e32 v131, v234, v224
	v_add_f32_e32 v130, v135, v130
	v_exp_f32_e32 v139, v131
	v_sub_f32_e32 v131, v232, v224
	v_add_f32_e32 v130, v136, v130
	v_exp_f32_e32 v140, v131
	v_sub_f32_e32 v131, v235, v224
	v_add_f32_e32 v130, v137, v130
	v_exp_f32_e32 v141, v131
	v_sub_f32_e32 v131, v236, v224
	v_add_f32_e32 v130, v138, v130
	v_exp_f32_e32 v142, v131
	v_sub_f32_e32 v131, v238, v224
	v_add_f32_e32 v130, v139, v130
	v_exp_f32_e32 v143, v131
	v_sub_f32_e32 v131, v237, v224
	v_add_f32_e32 v130, v140, v130
	v_exp_f32_e32 v144, v131
	v_sub_f32_e32 v131, v239, v224
	v_add_f32_e32 v130, v141, v130
	v_exp_f32_e32 v145, v131
	v_sub_f32_e32 v131, v240, v224
	v_add_f32_e32 v130, v142, v130
	v_exp_f32_e32 v225, v131
	v_sub_f32_e32 v131, v241, v224
	v_add_f32_e32 v130, v143, v130
	v_exp_f32_e32 v226, v131
	v_add_f32_e32 v130, v144, v130
	v_add_f32_e32 v130, v145, v130
	v_cvt_pk_bf16_f32 v132, v132, v133
	v_cvt_pk_bf16_f32 v133, v134, v135
	v_cvt_pk_bf16_f32 v134, v136, v137
	v_cvt_pk_bf16_f32 v136, v140, v141
	ds_read_b64_tr_b16 v[140:141], v0 offset:0
	v_add_f32_e32 v130, v225, v130
	v_cvt_pk_bf16_f32 v137, v142, v143
	ds_read_b64_tr_b16 v[142:143], v0 offset:0x800
	v_add_f32_e32 v130, v226, v130
	v_cvt_pk_bf16_f32 v135, v138, v139
	v_cvt_pk_bf16_f32 v139, v225, v226
	ds_read_b64_tr_b16 v[226:227], v0 offset:0x1000
	ds_read_b64_tr_b16 v[228:229], v0 offset:0x1800
	ds_read_b64_tr_b16 v[230:231], v0 offset:0x200
	ds_read_b64_tr_b16 v[232:233], v0 offset:0xa00
	ds_read_b64_tr_b16 v[234:235], v0 offset:0x1200
	ds_read_b64_tr_b16 v[236:237], v0 offset:0x1a00
	ds_read_b64_tr_b16 v[238:239], v0 offset:0x400
	ds_read_b64_tr_b16 v[240:241], v0 offset:0xc00
	ds_read_b64_tr_b16 v[242:243], v0 offset:0x1400
	ds_read_b64_tr_b16 v[244:245], v0 offset:0x1c00
	s_waitcnt lgkmcnt(8)
	v_mov_b32_e32 v131, v130
	s_nop 1
	v_permlane32_swap_b32_e32 v130, v131
	v_cvt_pk_bf16_f32 v138, v144, v145
	v_permlane32_swap_b32_e32 v132, v134
	v_permlane32_swap_b32_e32 v133, v135
	v_permlane32_swap_b32_e32 v136, v138
	v_permlane32_swap_b32_e32 v137, v139
	s_setprio 1
	v_mfma_f32_32x32x16_bf16 v[2:17], v[132:135], v[140:143], v[2:17]
	v_mfma_f32_32x32x16_bf16 v[2:17], v[136:139], v[226:229], v[2:17]
	s_setprio 0
	ds_read_b64_tr_b16 v[140:141], v0 offset:0x600
	ds_read_b64_tr_b16 v[142:143], v0 offset:0xe00
	ds_read_b64_tr_b16 v[226:227], v0 offset:0x1600
	ds_read_b64_tr_b16 v[228:229], v0 offset:0x1e00
	s_waitcnt lgkmcnt(8)
	s_setprio 1
	v_mfma_f32_32x32x16_bf16 v[18:33], v[132:135], v[230:233], v[18:33]
	v_mfma_f32_32x32x16_bf16 v[18:33], v[136:139], v[234:237], v[18:33]
	s_setprio 0
	ds_read_b64_tr_b16 v[230:231], v0 offset:0x4000
	ds_read_b64_tr_b16 v[232:233], v0 offset:0x4800
	ds_read_b64_tr_b16 v[234:235], v0 offset:0x5000
	ds_read_b64_tr_b16 v[236:237], v0 offset:0x5800
	s_waitcnt lgkmcnt(8)
	s_setprio 1
	v_mfma_f32_32x32x16_bf16 v[34:49], v[132:135], v[238:241], v[34:49]
	v_mfma_f32_32x32x16_bf16 v[34:49], v[136:139], v[242:245], v[34:49]
	s_setprio 0
	ds_read_b64_tr_b16 v[238:239], v0 offset:0x4200
	ds_read_b64_tr_b16 v[240:241], v0 offset:0x4a00
	ds_read_b64_tr_b16 v[242:243], v0 offset:0x5200
	ds_read_b64_tr_b16 v[244:245], v0 offset:0x5a00
	s_waitcnt lgkmcnt(8)
	s_setprio 1
	v_mfma_f32_32x32x16_bf16 v[50:65], v[132:135], v[140:143], v[50:65]
	v_mfma_f32_32x32x16_bf16 v[50:65], v[136:139], v[226:229], v[50:65]
	s_setprio 0
	ds_read_b64_tr_b16 v[140:141], v0 offset:0x4400
	ds_read_b64_tr_b16 v[142:143], v0 offset:0x4c00
	ds_read_b64_tr_b16 v[226:227], v0 offset:0x5400
	ds_read_b64_tr_b16 v[228:229], v0 offset:0x5c00
	s_waitcnt lgkmcnt(8)
	s_setprio 1
	v_mfma_f32_32x32x16_bf16 v[66:81], v[132:135], v[230:233], v[66:81]
	v_mfma_f32_32x32x16_bf16 v[66:81], v[136:139], v[234:237], v[66:81]
	s_setprio 0
	ds_read_b64_tr_b16 v[230:231], v0 offset:0x4600
	ds_read_b64_tr_b16 v[232:233], v0 offset:0x4e00
	ds_read_b64_tr_b16 v[234:235], v0 offset:0x5600
	ds_read_b64_tr_b16 v[236:237], v0 offset:0x5e00
	s_waitcnt lgkmcnt(8)
	s_setprio 1
	v_mfma_f32_32x32x16_bf16 v[82:97], v[132:135], v[238:241], v[82:97]
	v_mfma_f32_32x32x16_bf16 v[82:97], v[136:139], v[242:245], v[82:97]
	s_setprio 0
	s_waitcnt lgkmcnt(4)
	s_setprio 1
	v_mfma_f32_32x32x16_bf16 v[98:113], v[132:135], v[140:143], v[98:113]
	v_mfma_f32_32x32x16_bf16 v[98:113], v[136:139], v[226:229], v[98:113]
	s_setprio 0
	s_waitcnt lgkmcnt(0)
	s_setprio 1
	v_mfma_f32_32x32x16_bf16 v[114:129], v[132:135], v[230:233], v[114:129]
	v_mfma_f32_32x32x16_bf16 v[114:129], v[136:139], v[234:237], v[114:129]
	s_setprio 0
	s_andn2_b64 vcc, exec, s[24:25]
	s_mov_b64 s[34:35], 0
	s_cbranch_vccnz .LBB0_286
	ds_read_b32 v0, v205 offset:128
	v_add_u32_e32 v132, 33, v222
	v_cvt_f32_i32_e32 v132, v132
	s_mov_b32 s34, 0xc3160000
	s_waitcnt lgkmcnt(0)
	v_fma_f32 v0, -v194, v132, v0
	v_sub_f32_e32 v0, v0, v224
	v_cmp_gt_f32_e32 vcc, s34, v0
	s_cmp_eq_u64 vcc, exec
	s_cselect_b64 s[34:35], -1, 0
